# DPP: LayerNorm wave all-reduces (60 ds_bpermute hops) replaced by DPP quad_perm/row_mirror adds and v_permlane16/32_swap, no LDS round trips; on top of CONV5
# speedup vs baseline: 1.0101x; 1.0101x over previous
; __device__ __forceinline__ float bflo(unsigned w) { return __uint_as_float(w << 16); }
; __device__ __forceinline__ float bfhi(unsigned w) { return __uint_as_float(w & 0xffff0000u); }
; __device__ __forceinline__ float lane_get(float v, int src_lane) { return __int_as_float(__builtin_amdgcn_ds_bpermute(src_lane << 2, __float_as_int(v))); }
; __device__ __forceinline__ float wave_sum(float v, int lane) {
; #pragma unroll
;     for (int o = 1; o < 64; o <<= 1) v += lane_get(v, lane ^ o);
;     return v;
; }
; __device__ __forceinline__ void phase_ln2(const Params& p, int g, int gw, int NGW, int lane) {
;     ...
; #pragma unroll
;         for (int j = 0; j < 4; ++j) { const u32x2 bw = nb[j];
;             v[j] = nx[j] * ALPHA + (f32x4){bflo(bw.x), bfhi(bw.x), bflo(bw.y), bfhi(bw.y)}; s += (v[j].x + v[j].y) + (v[j].z + v[j].w); }
;         if (row + NGW < TG) { const size_t nr = (size_t)(row + NGW) * DM;
; #pragma unroll
;             for (int j = 0; j < 4; ++j) { nx[j] = *(const f32x4*)(x1base + nr + 4 * lane + 256 * j); nb[j] = *(const u32x2*)(brbase + nr + 4 * lane + 256 * j); } }
;         const float mean = wave_sum(s, lane) * (1.f / DM); float s2 = 0.f;
; #pragma unroll
;         for (int j = 0; j < 4; ++j) { v[j] = v[j] - mean; s2 += (v[j].x * v[j].x + v[j].y * v[j].y) + (v[j].z * v[j].z + v[j].w * v[j].w); }
;         const float rstd = __builtin_amdgcn_rsqf(wave_sum(s2, lane) * (1.f / DM) + 1e-6f);
; #pragma unroll
;         for (int j = 0; j < 4; ++j) { const int col = 4 * lane + 256 * j;
;             *(f32x4*)(xr + col) = v[j] * rstd * gaH[j] + beH[j]; }
.LBB0_236:
	v_lshlrev_b32_e32 v94, 16, v76
	v_and_b32_e32 v95, 0xffff0000, v76
	v_lshlrev_b32_e32 v76, 16, v77
	v_and_b32_e32 v77, 0xffff0000, v77
	v_pk_fma_f32 v[42:43], v[42:43], s[70:71], v[76:77] op_sel_hi:[1,0,1]
	v_pk_fma_f32 v[40:41], v[40:41], s[70:71], v[94:95] op_sel_hi:[1,0,1]
	v_add_f32_e32 v77, v42, v43
	v_add_f32_e32 v76, v40, v41
	v_add_f32_e32 v76, v76, v77
	v_add_f32_e32 v93, 0, v76
	v_lshlrev_b32_e32 v76, 16, v74
	v_and_b32_e32 v77, 0xffff0000, v74
	v_lshlrev_b32_e32 v74, 16, v75
	v_and_b32_e32 v75, 0xffff0000, v75
	v_pk_fma_f32 v[46:47], v[46:47], s[70:71], v[74:75] op_sel_hi:[1,0,1]
	v_pk_fma_f32 v[44:45], v[44:45], s[70:71], v[76:77] op_sel_hi:[1,0,1]
	v_add_f32_e32 v75, v46, v47
	v_add_f32_e32 v74, v44, v45
	v_add_f32_e32 v74, v74, v75
	v_add_f32_e32 v76, v74, v93
	v_lshlrev_b32_e32 v74, 16, v72
	v_and_b32_e32 v75, 0xffff0000, v72
	v_lshlrev_b32_e32 v72, 16, v73
	v_and_b32_e32 v73, 0xffff0000, v73
	v_pk_fma_f32 v[38:39], v[38:39], s[70:71], v[72:73] op_sel_hi:[1,0,1]
	v_pk_fma_f32 v[36:37], v[36:37], s[70:71], v[74:75] op_sel_hi:[1,0,1]
	v_add_f32_e32 v73, v38, v39
	v_add_f32_e32 v72, v36, v37
	v_add_f32_e32 v72, v72, v73
	v_add_f32_e32 v74, v72, v76
	v_lshlrev_b32_e32 v72, 16, v70
	v_and_b32_e32 v73, 0xffff0000, v70
	v_lshlrev_b32_e32 v70, 16, v71
	v_and_b32_e32 v71, 0xffff0000, v71
	v_pk_fma_f32 v[70:71], v[34:35], s[70:71], v[70:71] op_sel_hi:[1,0,1]
	v_pk_fma_f32 v[72:73], v[32:33], s[70:71], v[72:73] op_sel_hi:[1,0,1]
	v_add_f32_e32 v33, v70, v71
	v_add_f32_e32 v32, v72, v73
	v_add_f32_e32 v32, v32, v33
	v_add_f32_e32 v32, v32, v74
	v_readlane_b32 s4, v255, 0
	v_readlane_b32 s10, v255, 2
	v_readlane_b32 s5, v255, 1
	v_readlane_b32 s11, v255, 3
	s_nop 1
	v_add_f32_dpp v32, v32, v32 quad_perm:[1,0,3,2] row_mask:0xf bank_mask:0xf
	v_lshl_add_u64 v[64:65], v[64:65], 0, s[4:5]
	v_lshl_add_u64 v[66:67], v[66:67], 0, s[10:11]
	s_andn2_b64 vcc, exec, s[0:1]
	s_nop 1
	v_add_f32_dpp v32, v32, v32 quad_perm:[2,3,0,1] row_mask:0xf bank_mask:0xf
	s_nop 1
	v_add_f32_dpp v32, v32, v32 row_half_mirror row_mask:0xf bank_mask:0xf
	s_nop 1
	v_add_f32_dpp v32, v32, v32 row_mirror row_mask:0xf bank_mask:0xf
	v_mov_b32_e32 v33, v32
	s_nop 1
	v_permlane16_swap_b32_e32 v32, v33
	v_add_f32_e32 v32, v32, v33
	v_mov_b32_e32 v33, v32
	s_nop 1
	v_permlane32_swap_b32_e32 v32, v33
	v_add_f32_e32 v93, v32, v33
	v_fmamk_f32 v41, v93, 0xba800000, v41
	v_fmac_f32_e32 v40, 0xba800000, v93
	v_fmamk_f32 v43, v93, 0xba800000, v43
	v_fmac_f32_e32 v42, 0xba800000, v93
	v_pk_mul_f32 v[32:33], v[42:43], v[42:43]
	v_pk_mul_f32 v[34:35], v[40:41], v[40:41]
	v_fmamk_f32 v45, v93, 0xba800000, v45
	v_pk_mov_b32 v[74:75], v[34:35], v[32:33] op_sel:[1,0]
	v_mov_b32_e32 v35, v33
	v_pk_add_f32 v[32:33], v[74:75], v[34:35]
	v_fmac_f32_e32 v44, 0xba800000, v93
	v_fmamk_f32 v47, v93, 0xba800000, v47
	v_fmac_f32_e32 v46, 0xba800000, v93
	v_pk_add_f32 v[32:33], v[32:33], v[32:33] op_sel_hi:[0,1]
	v_pk_mul_f32 v[34:35], v[46:47], v[46:47]
	v_pk_mul_f32 v[74:75], v[44:45], v[44:45]
	v_fmac_f32_e32 v36, 0xba800000, v93
	v_pk_mov_b32 v[76:77], v[74:75], v[34:35] op_sel:[1,0]
	v_mov_b32_e32 v75, v35
	v_fmamk_f32 v37, v93, 0xba800000, v37
	v_fmac_f32_e32 v38, 0xba800000, v93
	v_mul_f32_e32 v32, v36, v36
	v_pk_add_f32 v[34:35], v[76:77], v[74:75]
	v_fmamk_f32 v39, v93, 0xba800000, v39
	v_pk_fma_f32 v[74:75], v[36:37], v[36:37], v[32:33] op_sel_hi:[1,1,0]
	v_mul_f32_e32 v32, v38, v38
	v_pk_add_f32 v[34:35], v[34:35], v[34:35] op_sel_hi:[0,1]
	v_pk_fma_f32 v[76:77], v[38:39], v[38:39], v[32:33] op_sel_hi:[1,1,0]
	v_fmamk_f32 v71, v93, 0xba800000, v71
	v_fmac_f32_e32 v70, 0xba800000, v93
	v_fmamk_f32 v73, v93, 0xba800000, v73
	v_fmac_f32_e32 v72, 0xba800000, v93
	v_mul_f32_e32 v74, v72, v72
	v_mul_f32_e32 v76, v73, v73
	v_mul_f32_e32 v32, v70, v70
	v_mul_f32_e32 v34, v71, v71
	v_pk_add_f32 v[74:75], v[74:75], v[76:77]
	v_pk_add_f32 v[32:33], v[32:33], v[34:35]
	s_waitcnt vmcnt(3)
	v_mov_b64_e32 v[76:77], v[84:85]
	v_pk_add_f32 v[32:33], v[74:75], v[32:33]
	s_nop 0
	v_add_f32_e32 v32, v32, v33
	s_nop 1
	v_add_f32_dpp v32, v32, v32 quad_perm:[1,0,3,2] row_mask:0xf bank_mask:0xf
	s_nop 1
	v_add_f32_dpp v32, v32, v32 quad_perm:[2,3,0,1] row_mask:0xf bank_mask:0xf
	s_nop 1
	v_add_f32_dpp v32, v32, v32 row_half_mirror row_mask:0xf bank_mask:0xf
	s_nop 1
	v_add_f32_dpp v32, v32, v32 row_mirror row_mask:0xf bank_mask:0xf
	v_mov_b32_e32 v33, v32
	s_nop 1
	v_permlane16_swap_b32_e32 v32, v33
	v_add_f32_e32 v32, v32, v33
	v_mov_b32_e32 v33, v32
	s_nop 1
	v_permlane32_swap_b32_e32 v32, v33
	v_add_f32_e32 v32, v32, v33
	v_fmamk_f32 v32, v32, 0x3a800000, v238
	v_rsq_f32_e32 v74, v32
	s_nop 0
	v_pk_mul_f32 v[32:33], v[40:41], v[74:75] op_sel_hi:[1,0]
	v_pk_mul_f32 v[34:35], v[42:43], v[74:75] op_sel_hi:[1,0]
	v_pk_fma_f32 v[32:33], v[0:1], v[32:33], v[4:5]
	v_pk_fma_f32 v[34:35], v[2:3], v[34:35], v[6:7]
	global_store_dwordx4 v[68:69], v[32:35], off
	v_mov_b32_e32 v40, v48
	v_mov_b32_e32 v41, v49
	v_pk_mul_f32 v[32:33], v[44:45], v[74:75] op_sel_hi:[1,0]
	v_pk_mul_f32 v[34:35], v[46:47], v[74:75] op_sel_hi:[1,0]
	v_pk_fma_f32 v[32:33], v[8:9], v[32:33], v[12:13]
	v_pk_fma_f32 v[34:35], v[10:11], v[34:35], v[14:15]
	global_store_dwordx4 v[68:69], v[32:35], off offset:1024
	v_mov_b32_e32 v42, v50
	v_mov_b32_e32 v43, v51
	v_pk_mul_f32 v[32:33], v[36:37], v[74:75] op_sel_hi:[1,0]
	v_pk_mul_f32 v[34:35], v[38:39], v[74:75] op_sel_hi:[1,0]
	v_pk_fma_f32 v[32:33], v[16:17], v[32:33], v[20:21]
	v_pk_fma_f32 v[34:35], v[18:19], v[34:35], v[22:23]
	global_store_dwordx4 v[68:69], v[32:35], off offset:2048
	v_mov_b32_e32 v44, v52
	v_mov_b32_e32 v45, v53
	v_pk_mul_f32 v[32:33], v[72:73], v[74:75] op_sel_hi:[1,0]
	v_pk_mul_f32 v[34:35], v[70:71], v[74:75] op_sel_hi:[1,0]
	v_pk_fma_f32 v[32:33], v[24:25], v[32:33], v[28:29]
	v_pk_fma_f32 v[34:35], v[26:27], v[34:35], v[30:31]
	global_store_dwordx4 v[68:69], v[32:35], off offset:3072
	v_lshl_add_u64 v[68:69], v[68:69], 0, s[4:5]
	s_waitcnt vmcnt(4)
	v_mov_b64_e32 v[70:71], v[78:79]
	v_mov_b64_e32 v[72:73], v[80:81]
	v_mov_b64_e32 v[74:75], v[82:83]
	v_mov_b32_e32 v46, v54
	v_mov_b32_e32 v47, v55
	v_mov_b32_e32 v36, v56
	v_mov_b32_e32 v37, v57
	v_mov_b32_e32 v38, v58
	v_mov_b32_e32 v39, v59
	v_mov_b32_e32 v32, v60
	v_mov_b32_e32 v33, v61
	v_mov_b32_e32 v34, v62
	v_mov_b32_e32 v35, v63
	s_cbranch_vccz .LBB0_239

; __device__ __forceinline__ unsigned cvt_pk_bf16(float lo, float hi) { unsigned r; asm volatile("s_nop 0\n\tv_cvt_pk_bf16_f32 %0, %1, %2\n\ts_nop 1" : "=v"(r) : "v"(lo), "v"(hi)); return r; }
; __device__ __forceinline__ float lane_get(float v, int src_lane) { return __int_as_float(__builtin_amdgcn_ds_bpermute(src_lane << 2, __float_as_int(v))); }
; __device__ __forceinline__ float wave_sum(float v, int lane) {
; #pragma unroll
;     for (int o = 1; o < 64; o <<= 1) v += lane_get(v, lane ^ o);
;     return v;
; }
; __device__ __forceinline__ void phase_ln0(const Params& p, int g, int gw, int NGW, int lane) {
;     ...
;         f32x4 v[4]; float s = 0.f;
; #pragma unroll
;         for (int j = 0; j < 4; ++j) { v[j] = nx[j]; s += (v[j].x + v[j].y) + (v[j].z + v[j].w); }
;         if (row + NGW < RG) { const float* src = ln0_src(p, g, row + NGW);
; #pragma unroll
;             for (int j = 0; j < 4; ++j) nx[j] = *(const f32x4*)(src + 4 * lane + 256 * j); }
;         const float mean = wave_sum(s, lane) * (1.f / DM); float s2 = 0.f;
; #pragma unroll
;         for (int j = 0; j < 4; ++j) { v[j] = v[j] - mean; s2 += (v[j].x * v[j].x + v[j].y * v[j].y) + (v[j].z * v[j].z + v[j].w * v[j].w); }
;         const float rstd = __builtin_amdgcn_rsqf(wave_sum(s2, lane) * (1.f / DM) + 1e-6f);
; #pragma unroll
;         for (int j = 0; j < 4; ++j) { const int col = 4 * lane + 256 * j; const f32x4 a = *(const f32x4*)(sc + col), b = *(const f32x4*)(sh + col);
;             const f32x4 o = v[j] * rstd * (a + 1.f) + b; u32x2 w; w.x = cvt_pk_bf16(o.x, o.y); w.y = cvt_pk_bf16(o.z, o.w);
;             *(u32x2*)(h0 + (size_t)row * DM + col) = w; }
.LBB0_242:
	v_add_f32_e32 v32, v28, v29
	v_add_f32_e32 v33, v30, v31
	v_add_f32_e32 v32, v32, v33
	v_add_f32_e32 v33, v8, v9
	v_add_f32_e32 v34, v10, v11
	v_add_f32_e32 v32, 0, v32
	v_add_f32_e32 v33, v33, v34
	v_add_f32_e32 v32, v33, v32
	v_add_f32_e32 v33, v4, v5
	v_add_f32_e32 v34, v6, v7
	v_add_f32_e32 v33, v33, v34
	v_add_f32_e32 v32, v33, v32
	v_add_f32_e32 v33, v0, v1
	v_add_f32_e32 v34, v2, v3
	v_add_f32_e32 v33, v33, v34
	v_add_f32_e32 v32, v33, v32
	s_lshl_b64 s[2:3], s[2:3], 2
	s_add_u32 s2, s94, s2
	s_addc_u32 s3, s95, s3
	s_add_u32 s4, s2, 0x1000
	s_nop 1
	v_add_f32_dpp v32, v32, v32 quad_perm:[1,0,3,2] row_mask:0xf bank_mask:0xf
	s_addc_u32 s5, s3, 0
	s_andn2_b64 vcc, exec, s[0:1]
	s_nop 1
	v_add_f32_dpp v32, v32, v32 quad_perm:[2,3,0,1] row_mask:0xf bank_mask:0xf
	s_nop 1
	v_add_f32_dpp v32, v32, v32 row_half_mirror row_mask:0xf bank_mask:0xf
	s_nop 1
	v_add_f32_dpp v32, v32, v32 row_mirror row_mask:0xf bank_mask:0xf
	v_mov_b32_e32 v33, v32
	s_nop 1
	v_permlane16_swap_b32_e32 v32, v33
	v_add_f32_e32 v32, v32, v33
	v_mov_b32_e32 v33, v32
	s_nop 1
	v_permlane32_swap_b32_e32 v32, v33
	v_add_f32_e32 v38, v32, v33
	v_fmac_f32_e32 v29, 0xba800000, v38
	v_fmac_f32_e32 v28, 0xba800000, v38
	v_fmac_f32_e32 v31, 0xba800000, v38
	v_fmac_f32_e32 v30, 0xba800000, v38
	v_pk_mul_f32 v[32:33], v[30:31], v[30:31]
	v_pk_mul_f32 v[34:35], v[28:29], v[28:29]
	v_fmac_f32_e32 v9, 0xba800000, v38
	v_pk_mov_b32 v[50:51], v[34:35], v[32:33] op_sel:[1,0]
	v_mov_b32_e32 v35, v33
	v_pk_add_f32 v[32:33], v[50:51], v[34:35]
	v_fmac_f32_e32 v8, 0xba800000, v38
	v_fmac_f32_e32 v11, 0xba800000, v38
	v_fmac_f32_e32 v10, 0xba800000, v38
	v_pk_add_f32 v[32:33], v[32:33], v[32:33] op_sel_hi:[0,1]
	v_pk_mul_f32 v[34:35], v[10:11], v[10:11]
	v_pk_mul_f32 v[50:51], v[8:9], v[8:9]
	v_fmac_f32_e32 v4, 0xba800000, v38
	v_pk_mov_b32 v[52:53], v[50:51], v[34:35] op_sel:[1,0]
	v_mov_b32_e32 v51, v35
	v_fmac_f32_e32 v5, 0xba800000, v38
	v_fmac_f32_e32 v6, 0xba800000, v38
	v_mul_f32_e32 v32, v4, v4
	v_pk_add_f32 v[34:35], v[52:53], v[50:51]
	v_fmac_f32_e32 v7, 0xba800000, v38
	v_pk_fma_f32 v[50:51], v[4:5], v[4:5], v[32:33] op_sel_hi:[1,1,0]
	v_mul_f32_e32 v32, v6, v6
	v_pk_add_f32 v[34:35], v[34:35], v[34:35] op_sel_hi:[0,1]
	v_pk_fma_f32 v[52:53], v[6:7], v[6:7], v[32:33] op_sel_hi:[1,1,0]
	v_fmac_f32_e32 v3, 0xba800000, v38
	v_fmac_f32_e32 v2, 0xba800000, v38
	v_fmac_f32_e32 v1, 0xba800000, v38
	v_fmac_f32_e32 v0, 0xba800000, v38
	v_mul_f32_e32 v50, v0, v0
	v_mul_f32_e32 v52, v1, v1
	v_mul_f32_e32 v32, v2, v2
	v_mul_f32_e32 v34, v3, v3
	v_pk_add_f32 v[50:51], v[50:51], v[52:53]
	v_pk_add_f32 v[32:33], v[32:33], v[34:35]
	s_nop 0
	v_pk_add_f32 v[32:33], v[50:51], v[32:33]
	s_nop 0
	v_add_f32_e32 v32, v32, v33
	s_nop 1
	v_add_f32_dpp v32, v32, v32 quad_perm:[1,0,3,2] row_mask:0xf bank_mask:0xf
	s_nop 1
	v_add_f32_dpp v32, v32, v32 quad_perm:[2,3,0,1] row_mask:0xf bank_mask:0xf
	s_nop 1
	v_add_f32_dpp v32, v32, v32 row_half_mirror row_mask:0xf bank_mask:0xf
	s_nop 1
	v_add_f32_dpp v32, v32, v32 row_mirror row_mask:0xf bank_mask:0xf
	v_mov_b32_e32 v33, v32
	s_nop 1
	v_permlane16_swap_b32_e32 v32, v33
	v_add_f32_e32 v32, v32, v33
	v_mov_b32_e32 v33, v32
	s_nop 1
	v_permlane32_swap_b32_e32 v32, v33
	v_add_f32_e32 v32, v32, v33
	v_fmamk_f32 v32, v32, 0x3a800000, v238
	v_rsq_f32_e32 v38, v32
	global_load_dwordx4 v[32:35], v39, s[4:5]
	global_load_dwordx4 v[50:53], v39, s[2:3]
	global_load_dwordx4 v[100:103], v46, s[4:5]
	global_load_dwordx4 v[104:107], v39, s[2:3] offset:1024
	global_load_dwordx4 v[108:111], v47, s[4:5]
	global_load_dwordx4 v[112:115], v39, s[2:3] offset:2048
	global_load_dwordx4 v[116:119], v48, s[4:5]
	global_load_dwordx4 v[120:123], v39, s[2:3] offset:3072
	v_pk_mul_f32 v[28:29], v[28:29], v[38:39] op_sel_hi:[1,0]
	v_pk_mul_f32 v[30:31], v[30:31], v[38:39] op_sel_hi:[1,0]
	v_pk_mul_f32 v[8:9], v[8:9], v[38:39] op_sel_hi:[1,0]
	v_pk_mul_f32 v[10:11], v[10:11], v[38:39] op_sel_hi:[1,0]
	v_pk_mul_f32 v[4:5], v[4:5], v[38:39] op_sel_hi:[1,0]
	v_pk_mul_f32 v[6:7], v[6:7], v[38:39] op_sel_hi:[1,0]
	v_pk_mul_f32 v[0:1], v[0:1], v[38:39] op_sel_hi:[1,0]
	v_pk_mul_f32 v[2:3], v[2:3], v[38:39] op_sel_hi:[1,0]
	s_waitcnt vmcnt(0)
	v_pk_add_f32 v[32:33], v[32:33], 1.0 op_sel_hi:[1,0]
	v_pk_add_f32 v[34:35], v[34:35], 1.0 op_sel_hi:[1,0]
	v_pk_fma_f32 v[28:29], v[32:33], v[28:29], v[50:51]
	v_pk_fma_f32 v[30:31], v[34:35], v[30:31], v[52:53]
	v_cvt_pk_bf16_f32 v28, v28, v29
	s_nop 0
	v_cvt_pk_bf16_f32 v29, v30, v31
	global_store_dwordx2 v[36:37], v[28:29], off
	s_nop 0
	v_pk_add_f32 v[28:29], v[100:101], 1.0 op_sel_hi:[1,0]
	v_pk_add_f32 v[30:31], v[102:103], 1.0 op_sel_hi:[1,0]
	v_pk_fma_f32 v[8:9], v[28:29], v[8:9], v[104:105]
	v_pk_fma_f32 v[10:11], v[30:31], v[10:11], v[106:107]
	v_cvt_pk_bf16_f32 v8, v8, v9
	s_nop 0
	v_cvt_pk_bf16_f32 v9, v10, v11
	global_store_dwordx2 v[36:37], v[8:9], off offset:512
	s_nop 0
	v_pk_add_f32 v[8:9], v[108:109], 1.0 op_sel_hi:[1,0]
	v_pk_add_f32 v[10:11], v[110:111], 1.0 op_sel_hi:[1,0]
	v_pk_fma_f32 v[4:5], v[8:9], v[4:5], v[112:113]
	v_pk_fma_f32 v[6:7], v[10:11], v[6:7], v[114:115]
	v_cvt_pk_bf16_f32 v4, v4, v5
	v_mov_b32_e32 v28, v16
	v_cvt_pk_bf16_f32 v5, v6, v7
	global_store_dwordx2 v[36:37], v[4:5], off offset:1024
	s_nop 0
	v_readlane_b32 s2, v255, 2
	v_readlane_b32 s3, v255, 3
	v_mov_b32_e32 v29, v17
	v_mov_b32_e32 v30, v18
	v_mov_b32_e32 v31, v19
	v_pk_add_f32 v[4:5], v[116:117], 1.0 op_sel_hi:[1,0]
	v_pk_add_f32 v[6:7], v[118:119], 1.0 op_sel_hi:[1,0]
	v_pk_fma_f32 v[0:1], v[4:5], v[0:1], v[120:121]
	v_pk_fma_f32 v[2:3], v[6:7], v[2:3], v[122:123]
	v_cvt_pk_bf16_f32 v0, v0, v1
	v_mov_b32_e32 v8, v20
	v_cvt_pk_bf16_f32 v1, v2, v3
	global_store_dwordx2 v[36:37], v[0:1], off offset:1536
	v_lshl_add_u64 v[36:37], v[36:37], 0, s[2:3]
	v_mov_b32_e32 v9, v21
	v_mov_b32_e32 v10, v22
	v_mov_b32_e32 v11, v23
	v_mov_b32_e32 v4, v24
	v_mov_b32_e32 v5, v25
	v_mov_b32_e32 v6, v26
	v_mov_b32_e32 v7, v27
	v_mov_b32_e32 v0, v12
	v_mov_b32_e32 v1, v13
	v_mov_b32_e32 v2, v14
	v_mov_b32_e32 v3, v15
	s_cbranch_vccz .LBB0_247

; __device__ __forceinline__ float bflo(unsigned w) { return __uint_as_float(w << 16); }
; __device__ __forceinline__ float bfhi(unsigned w) { return __uint_as_float(w & 0xffff0000u); }
; __device__ __forceinline__ void phase_ln1(const Params& p, int g, int gw, int NGW, int lane) {
;     ...
;         f32x4 v[4]; float s = 0.f;
; #pragma unroll
;         for (int j = 0; j < 4; ++j) { const u32x2 bw = nb[j];
;             v[j] = nx[j] * ALPHA + (f32x4){bflo(bw.x), bfhi(bw.x), bflo(bw.y), bfhi(bw.y)}; s += (v[j].x + v[j].y) + (v[j].z + v[j].w); }
;         if (row + NGW < TG) { const size_t nr = (size_t)(row + NGW) * DM;
; #pragma unroll
;             for (int j = 0; j < 4; ++j) { nx[j] = *(const f32x4*)(xbase + nr + 4 * lane + 256 * j); nb[j] = *(const u32x2*)(brbase + nr + 4 * lane + 256 * j); } }
;         float mean = wave_sum(s, lane) * (1.f / DM); float s2 = 0.f;
; #pragma unroll
;         for (int j = 0; j < 4; ++j) { v[j] = v[j] - mean; s2 += (v[j].x * v[j].x + v[j].y * v[j].y) + (v[j].z * v[j].z + v[j].w * v[j].w); }
;         float rstd = __builtin_amdgcn_rsqf(wave_sum(s2, lane) * (1.f / DM) + 1e-6f);
;         s = 0.f;
; #pragma unroll
;         for (int j = 0; j < 4; ++j) { const int col = 4 * lane + 256 * j; const f32x4 ga = gaH[j], be = beH[j];
;             v[j] = v[j] * rstd * ga + be; *(f32x4*)(xr + col) = v[j]; s += (v[j].x + v[j].y) + (v[j].z + v[j].w); }
.LBB0_305:
	v_lshlrev_b32_e32 v98, 16, v86
	v_and_b32_e32 v99, 0xffff0000, v86
	v_lshlrev_b32_e32 v86, 16, v87
	v_and_b32_e32 v87, 0xffff0000, v87
	v_pk_fma_f32 v[62:63], v[62:63], s[70:71], v[86:87] op_sel_hi:[1,0,1]
	v_pk_fma_f32 v[60:61], v[60:61], s[70:71], v[98:99] op_sel_hi:[1,0,1]
	v_add_f32_e32 v87, v62, v63
	v_add_f32_e32 v86, v60, v61
	v_add_f32_e32 v86, v86, v87
	v_add_f32_e32 v98, 0, v86
	v_lshlrev_b32_e32 v86, 16, v84
	v_and_b32_e32 v87, 0xffff0000, v84
	v_lshlrev_b32_e32 v84, 16, v85
	v_and_b32_e32 v85, 0xffff0000, v85
	v_pk_fma_f32 v[58:59], v[58:59], s[70:71], v[84:85] op_sel_hi:[1,0,1]
	v_pk_fma_f32 v[56:57], v[56:57], s[70:71], v[86:87] op_sel_hi:[1,0,1]
	v_add_f32_e32 v85, v58, v59
	v_add_f32_e32 v84, v56, v57
	v_add_f32_e32 v84, v84, v85
	v_add_f32_e32 v86, v84, v98
	v_lshlrev_b32_e32 v84, 16, v82
	v_and_b32_e32 v85, 0xffff0000, v82
	v_lshlrev_b32_e32 v82, 16, v83
	v_and_b32_e32 v83, 0xffff0000, v83
	v_pk_fma_f32 v[82:83], v[54:55], s[70:71], v[82:83] op_sel_hi:[1,0,1]
	v_pk_fma_f32 v[84:85], v[52:53], s[70:71], v[84:85] op_sel_hi:[1,0,1]
	v_add_f32_e32 v53, v82, v83
	v_add_f32_e32 v52, v84, v85
	v_add_f32_e32 v52, v52, v53
	v_add_f32_e32 v98, v52, v86
	v_lshlrev_b32_e32 v52, 16, v80
	v_and_b32_e32 v53, 0xffff0000, v80
	v_lshlrev_b32_e32 v54, 16, v81
	v_and_b32_e32 v55, 0xffff0000, v81
	v_pk_fma_f32 v[80:81], v[50:51], s[70:71], v[54:55] op_sel_hi:[1,0,1]
	v_pk_fma_f32 v[86:87], v[48:49], s[70:71], v[52:53] op_sel_hi:[1,0,1]
	v_add_f32_e32 v49, v80, v81
	v_add_f32_e32 v48, v86, v87
	v_add_f32_e32 v48, v48, v49
	v_add_f32_e32 v48, v48, v98
	s_ashr_i32 s1, s4, 31
	s_lshr_b32 s1, s1, 21
	s_add_i32 s1, s4, s1
	s_ashr_i32 s1, s1, 11
	s_nop 1
	v_add_f32_dpp v48, v48, v48 quad_perm:[1,0,3,2] row_mask:0xf bank_mask:0xf
	s_add_i32 s1, s1, s76
	s_mul_hi_i32 s4, s1, 0x6000
	s_mulk_i32 s1, 0x6000
	s_add_u32 s1, s94, s1
	s_nop 1
	v_add_f32_dpp v48, v48, v48 quad_perm:[2,3,0,1] row_mask:0xf bank_mask:0xf
	s_addc_u32 s7, s95, s4
	s_add_u32 s4, s1, 0x3000
	s_addc_u32 s5, s7, 0
	s_add_u32 s6, s1, 0x4000
	s_nop 1
	v_add_f32_dpp v48, v48, v48 row_half_mirror row_mask:0xf bank_mask:0xf
	s_addc_u32 s7, s7, 0
	s_mov_b32 s1, 0xf900000
	s_nop 1
	v_add_f32_dpp v48, v48, v48 row_mirror row_mask:0xf bank_mask:0xf
	v_mov_b32_e32 v49, v48
	s_nop 1
	v_permlane16_swap_b32_e32 v48, v49
	v_add_f32_e32 v48, v48, v49
	v_mov_b32_e32 v49, v48
	s_nop 1
	v_permlane32_swap_b32_e32 v48, v49
	v_add_f32_e32 v98, v48, v49
	v_fmamk_f32 v61, v98, 0xba800000, v61
	v_fmac_f32_e32 v60, 0xba800000, v98
	v_fmamk_f32 v63, v98, 0xba800000, v63
	v_fmac_f32_e32 v62, 0xba800000, v98
	v_pk_mul_f32 v[48:49], v[62:63], v[62:63]
	v_pk_mul_f32 v[50:51], v[60:61], v[60:61]
	v_fmamk_f32 v57, v98, 0xba800000, v57
	v_pk_mov_b32 v[52:53], v[50:51], v[48:49] op_sel:[1,0]
	v_mov_b32_e32 v51, v49
	v_pk_add_f32 v[48:49], v[52:53], v[50:51]
	v_fmac_f32_e32 v56, 0xba800000, v98
	v_fmamk_f32 v59, v98, 0xba800000, v59
	v_fmac_f32_e32 v58, 0xba800000, v98
	v_pk_add_f32 v[48:49], v[48:49], v[48:49] op_sel_hi:[0,1]
	v_pk_mul_f32 v[50:51], v[58:59], v[58:59]
	v_pk_mul_f32 v[52:53], v[56:57], v[56:57]
	v_fmac_f32_e32 v84, 0xba800000, v98
	v_pk_mov_b32 v[54:55], v[52:53], v[50:51] op_sel:[1,0]
	v_mov_b32_e32 v53, v51
	v_fmamk_f32 v85, v98, 0xba800000, v85
	v_fmac_f32_e32 v82, 0xba800000, v98
	v_mul_f32_e32 v48, v84, v84
	v_pk_add_f32 v[50:51], v[54:55], v[52:53]
	v_fmamk_f32 v83, v98, 0xba800000, v83
	v_pk_fma_f32 v[52:53], v[84:85], v[84:85], v[48:49] op_sel_hi:[1,1,0]
	v_mul_f32_e32 v48, v82, v82
	v_pk_add_f32 v[50:51], v[50:51], v[50:51] op_sel_hi:[0,1]
	v_pk_fma_f32 v[54:55], v[82:83], v[82:83], v[48:49] op_sel_hi:[1,1,0]
	v_fmamk_f32 v81, v98, 0xba800000, v81
	v_fmac_f32_e32 v80, 0xba800000, v98
	v_fmamk_f32 v87, v98, 0xba800000, v87
	v_fmac_f32_e32 v86, 0xba800000, v98
	v_mul_f32_e32 v52, v86, v86
	v_mul_f32_e32 v54, v87, v87
	v_mul_f32_e32 v48, v80, v80
	v_mul_f32_e32 v50, v81, v81
	v_pk_add_f32 v[52:53], v[52:53], v[54:55]
	v_pk_add_f32 v[48:49], v[48:49], v[50:51]
	s_nop 0
	v_pk_add_f32 v[48:49], v[52:53], v[48:49]
	v_lshl_add_u64 v[52:53], s[94:95], 0, v[68:69]
	v_add_f32_e32 v48, v48, v49
	v_add_co_u32_e32 v100, vcc, s89, v52
	s_nop 1
	v_add_f32_dpp v48, v48, v48 quad_perm:[1,0,3,2] row_mask:0xf bank_mask:0xf
	v_addc_co_u32_e32 v101, vcc, 0, v53, vcc
	s_nop 1
	v_add_f32_dpp v48, v48, v48 quad_perm:[2,3,0,1] row_mask:0xf bank_mask:0xf
	s_nop 1
	v_add_f32_dpp v48, v48, v48 row_half_mirror row_mask:0xf bank_mask:0xf
	s_nop 1
	v_add_f32_dpp v48, v48, v48 row_mirror row_mask:0xf bank_mask:0xf
	v_mov_b32_e32 v49, v48
	s_nop 1
	v_permlane16_swap_b32_e32 v48, v49
	v_add_f32_e32 v48, v48, v49
	v_mov_b32_e32 v49, v48
	s_nop 1
	v_permlane32_swap_b32_e32 v48, v49
	v_add_f32_e32 v48, v48, v49
	v_fmamk_f32 v48, v48, 0x3a800000, v238
	v_rsq_f32_e32 v98, v48
	s_nop 0
	v_pk_mul_f32 v[50:51], v[62:63], v[98:99] op_sel_hi:[1,0]
	v_pk_mul_f32 v[48:49], v[60:61], v[98:99] op_sel_hi:[1,0]
	v_pk_fma_f32 v[50:51], v[2:3], v[50:51], v[6:7]
	v_pk_fma_f32 v[48:49], v[0:1], v[48:49], v[4:5]
	v_mov_b32_e32 v55, v51
	v_pk_mov_b32 v[52:53], v[48:49], v[50:51] op_sel:[1,0]
	v_mov_b32_e32 v54, v48
	v_pk_add_f32 v[52:53], v[52:53], v[54:55]
	global_store_dwordx4 v[100:101], v[48:51], off
	v_add_f32_e32 v52, v52, v53
	v_add_f32_e32 v99, 0, v52
	v_pk_mul_f32 v[54:55], v[58:59], v[98:99] op_sel_hi:[1,0]
	v_pk_mul_f32 v[52:53], v[56:57], v[98:99] op_sel_hi:[1,0]
	v_pk_fma_f32 v[54:55], v[10:11], v[54:55], v[14:15]
	v_pk_fma_f32 v[52:53], v[8:9], v[52:53], v[12:13]
	v_mov_b32_e32 v59, v55
	v_pk_mov_b32 v[56:57], v[52:53], v[54:55] op_sel:[1,0]
	v_mov_b32_e32 v58, v52
	v_pk_add_f32 v[56:57], v[56:57], v[58:59]
; __device__ __forceinline__ unsigned cvt_pk_bf16(float lo, float hi) { unsigned r; asm volatile("s_nop 0\n\tv_cvt_pk_bf16_f32 %0, %1, %2\n\ts_nop 1" : "=v"(r) : "v"(lo), "v"(hi)); return r; }
; __device__ __forceinline__ void phase_ln1(const Params& p, int g, int gw, int NGW, int lane) {
;     ...
;             v[j] = v[j] * rstd * ga + be; *(f32x4*)(xr + col) = v[j]; s += (v[j].x + v[j].y) + (v[j].z + v[j].w); }
;         mean = wave_sum(s, lane) * (1.f / DM); s2 = 0.f;
; #pragma unroll
;         for (int j = 0; j < 4; ++j) { v[j] = v[j] - mean; s2 += (v[j].x * v[j].x + v[j].y * v[j].y) + (v[j].z * v[j].z + v[j].w * v[j].w); }
;         rstd = __builtin_amdgcn_rsqf(wave_sum(s2, lane) * (1.f / DM) + 1e-6f);
; #pragma unroll
;         for (int j = 0; j < 4; ++j) { const int col = 4 * lane + 256 * j; const f32x4 a = *(const f32x4*)(sc + col), bb = *(const f32x4*)(sh + col);
;             const f32x4 o = v[j] * rstd * (a + 1.f) + bb; u32x2 w; w.x = cvt_pk_bf16(o.x, o.y); w.y = cvt_pk_bf16(o.z, o.w);
;             *(u32x2*)(h1 + (size_t)row * DM + col) = w; }
	v_pk_mul_f32 v[58:59], v[82:83], v[98:99] op_sel_hi:[1,0]
	v_pk_add_f32 v[102:103], v[56:57], v[56:57] op_sel_hi:[0,1]
	v_pk_mul_f32 v[56:57], v[84:85], v[98:99] op_sel_hi:[1,0]
	v_pk_mul_f32 v[60:61], v[86:87], v[98:99] op_sel_hi:[1,0]
	v_pk_mul_f32 v[62:63], v[80:81], v[98:99] op_sel_hi:[1,0]
	v_pk_fma_f32 v[56:57], v[16:17], v[56:57], v[20:21]
	v_pk_fma_f32 v[58:59], v[18:19], v[58:59], v[22:23]
	v_pk_fma_f32 v[62:63], v[26:27], v[62:63], v[30:31]
	v_pk_fma_f32 v[60:61], v[24:25], v[60:61], v[28:29]
	v_add_f32_e32 v83, v56, v57
	v_add_f32_e32 v85, v58, v59
	v_mov_b32_e32 v82, v60
	v_mov_b32_e32 v84, v61
	v_mov_b32_e32 v102, v62
	v_mov_b32_e32 v98, v63
	v_pk_add_f32 v[80:81], v[82:83], v[84:85]
	v_pk_add_f32 v[82:83], v[102:103], v[98:99]
	global_store_dwordx4 v[100:101], v[52:55], off offset:1024
	v_pk_add_f32 v[80:81], v[80:81], v[82:83]
	global_store_dwordx4 v[100:101], v[56:59], off offset:2048
	v_add_f32_e32 v80, v80, v81
	global_store_dwordx4 v[100:101], v[60:63], off offset:3072
	s_nop 1
	v_add_f32_dpp v80, v80, v80 quad_perm:[1,0,3,2] row_mask:0xf bank_mask:0xf
	s_nop 1
	v_add_f32_dpp v80, v80, v80 quad_perm:[2,3,0,1] row_mask:0xf bank_mask:0xf
	s_nop 1
	v_add_f32_dpp v80, v80, v80 row_half_mirror row_mask:0xf bank_mask:0xf
	s_nop 1
	v_add_f32_dpp v80, v80, v80 row_mirror row_mask:0xf bank_mask:0xf
	v_mov_b32_e32 v81, v80
	s_nop 1
	v_permlane16_swap_b32_e32 v80, v81
	v_add_f32_e32 v80, v80, v81
	v_mov_b32_e32 v81, v80
	s_nop 1
	v_permlane32_swap_b32_e32 v80, v81
	v_add_f32_e32 v98, v80, v81
	v_fmamk_f32 v49, v98, 0xba800000, v49
	v_fmac_f32_e32 v48, 0xba800000, v98
	v_fmamk_f32 v51, v98, 0xba800000, v51
	v_fmac_f32_e32 v50, 0xba800000, v98
	v_pk_mul_f32 v[80:81], v[50:51], v[50:51]
	v_pk_mul_f32 v[82:83], v[48:49], v[48:49]
	v_fmamk_f32 v53, v98, 0xba800000, v53
	v_pk_mov_b32 v[84:85], v[82:83], v[80:81] op_sel:[1,0]
	v_mov_b32_e32 v83, v81
	v_pk_add_f32 v[80:81], v[84:85], v[82:83]
	v_fmac_f32_e32 v52, 0xba800000, v98
	v_fmamk_f32 v55, v98, 0xba800000, v55
	v_fmac_f32_e32 v54, 0xba800000, v98
	v_pk_add_f32 v[80:81], v[80:81], v[80:81] op_sel_hi:[0,1]
	v_pk_mul_f32 v[82:83], v[54:55], v[54:55]
	v_pk_mul_f32 v[84:85], v[52:53], v[52:53]
	v_fmac_f32_e32 v56, 0xba800000, v98
	v_pk_mov_b32 v[86:87], v[84:85], v[82:83] op_sel:[1,0]
	v_mov_b32_e32 v85, v83
	v_fmamk_f32 v57, v98, 0xba800000, v57
	v_fmac_f32_e32 v58, 0xba800000, v98
	v_mul_f32_e32 v80, v56, v56
	v_pk_add_f32 v[82:83], v[86:87], v[84:85]
	v_fmamk_f32 v59, v98, 0xba800000, v59
	v_pk_fma_f32 v[84:85], v[56:57], v[56:57], v[80:81] op_sel_hi:[1,1,0]
	v_mul_f32_e32 v80, v58, v58
	v_pk_add_f32 v[82:83], v[82:83], v[82:83] op_sel_hi:[0,1]
	v_pk_fma_f32 v[86:87], v[58:59], v[58:59], v[80:81] op_sel_hi:[1,1,0]
	v_fmamk_f32 v63, v98, 0xba800000, v63
	v_fmac_f32_e32 v62, 0xba800000, v98
	v_fmamk_f32 v61, v98, 0xba800000, v61
	v_fmac_f32_e32 v60, 0xba800000, v98
	v_mul_f32_e32 v84, v60, v60
	v_mul_f32_e32 v86, v61, v61
	v_mul_f32_e32 v80, v62, v62
	v_mul_f32_e32 v82, v63, v63
	v_pk_add_f32 v[84:85], v[84:85], v[86:87]
	v_pk_add_f32 v[80:81], v[80:81], v[82:83]
	s_nop 0
	v_pk_add_f32 v[80:81], v[84:85], v[80:81]
	global_load_dwordx4 v[82:85], v94, s[6:7]
	global_load_dwordx4 v[98:101], v94, s[4:5]
	global_load_dwordx4 v[104:107], v95, s[6:7]
	global_load_dwordx4 v[108:111], v95, s[4:5]
	global_load_dwordx4 v[112:115], v96, s[6:7]
	global_load_dwordx4 v[116:119], v96, s[4:5]
	global_load_dwordx4 v[120:123], v97, s[6:7]
	global_load_dwordx4 v[124:127], v97, s[4:5]
	v_add_f32_e32 v80, v80, v81
	s_nop 1
	v_add_f32_dpp v80, v80, v80 quad_perm:[1,0,3,2] row_mask:0xf bank_mask:0xf
	s_nop 1
	v_add_f32_dpp v80, v80, v80 quad_perm:[2,3,0,1] row_mask:0xf bank_mask:0xf
	s_nop 1
	v_add_f32_dpp v80, v80, v80 row_half_mirror row_mask:0xf bank_mask:0xf
	s_nop 1
	v_add_f32_dpp v80, v80, v80 row_mirror row_mask:0xf bank_mask:0xf
	v_mov_b32_e32 v81, v80
	s_nop 1
	v_permlane16_swap_b32_e32 v80, v81
	v_add_f32_e32 v80, v80, v81
	v_mov_b32_e32 v81, v80
	s_nop 1
	v_permlane32_swap_b32_e32 v80, v81
	v_add_f32_e32 v80, v80, v81
	v_fmamk_f32 v80, v80, 0x3a800000, v238
	v_rsq_f32_e32 v80, v80
	s_waitcnt vmcnt(0)
	v_pk_add_f32 v[84:85], v[84:85], 1.0 op_sel_hi:[1,0]
	v_pk_mul_f32 v[48:49], v[48:49], v[80:81] op_sel_hi:[1,0]
	v_pk_mul_f32 v[50:51], v[50:51], v[80:81] op_sel_hi:[1,0]
	v_pk_add_f32 v[82:83], v[82:83], 1.0 op_sel_hi:[1,0]
	v_pk_fma_f32 v[50:51], v[84:85], v[50:51], v[100:101]
	v_pk_fma_f32 v[48:49], v[82:83], v[48:49], v[98:99]
	v_pk_mul_f32 v[52:53], v[52:53], v[80:81] op_sel_hi:[1,0]
	v_cvt_pk_bf16_f32 v48, v48, v49
	v_cvt_pk_bf16_f32 v49, v50, v51
	v_lshl_add_u64 v[50:51], s[94:95], 0, v[70:71]
	v_add_co_u32_e32 v86, vcc, s1, v50
	v_pk_mul_f32 v[54:55], v[54:55], v[80:81] op_sel_hi:[1,0]
	s_nop 0
	v_addc_co_u32_e32 v87, vcc, 0, v51, vcc
	global_store_dwordx2 v[86:87], v[48:49], off
	s_nop 0
	v_pk_mul_f32 v[56:57], v[56:57], v[80:81] op_sel_hi:[1,0]
	v_pk_mul_f32 v[58:59], v[58:59], v[80:81] op_sel_hi:[1,0]
	s_and_b64 vcc, exec, s[2:3]
	v_pk_add_f32 v[48:49], v[104:105], 1.0 op_sel_hi:[1,0]
	v_pk_add_f32 v[50:51], v[106:107], 1.0 op_sel_hi:[1,0]
	v_pk_fma_f32 v[48:49], v[48:49], v[52:53], v[108:109]
	v_pk_fma_f32 v[50:51], v[50:51], v[54:55], v[110:111]
	v_cvt_pk_bf16_f32 v48, v48, v49
	v_mov_b64_e32 v[82:83], v[74:75]
	v_cvt_pk_bf16_f32 v49, v50, v51
	global_store_dwordx2 v[86:87], v[48:49], off offset:512
	s_nop 0
	v_mov_b64_e32 v[84:85], v[76:77]
	v_pk_add_f32 v[48:49], v[112:113], 1.0 op_sel_hi:[1,0]
	v_pk_add_f32 v[50:51], v[114:115], 1.0 op_sel_hi:[1,0]
	v_pk_fma_f32 v[48:49], v[48:49], v[56:57], v[116:117]
	v_pk_fma_f32 v[50:51], v[50:51], v[58:59], v[118:119]
	v_cvt_pk_bf16_f32 v48, v48, v49
	v_pk_mul_f32 v[56:57], v[60:61], v[80:81] op_sel_hi:[1,0]
	v_cvt_pk_bf16_f32 v49, v50, v51
	global_store_dwordx2 v[86:87], v[48:49], off offset:1024
	s_nop 0
	v_readlane_b32 s4, v255, 2
	v_readlane_b32 s5, v255, 3
	v_pk_mul_f32 v[58:59], v[62:63], v[80:81] op_sel_hi:[1,0]
	v_mov_b64_e32 v[80:81], v[72:73]
	v_lshl_add_u64 v[70:71], v[70:71], 0, s[4:5]
	v_readlane_b32 s4, v255, 0
	v_readlane_b32 s5, v255, 1
	v_mov_b32_e32 v60, v32
	v_mov_b32_e32 v61, v33
	v_lshl_add_u64 v[68:69], v[68:69], 0, s[4:5]
	s_mov_b32 s4, s0
	v_mov_b32_e32 v62, v34
	v_mov_b32_e32 v63, v35
	v_pk_add_f32 v[48:49], v[120:121], 1.0 op_sel_hi:[1,0]
	v_pk_add_f32 v[50:51], v[122:123], 1.0 op_sel_hi:[1,0]
	v_pk_fma_f32 v[48:49], v[48:49], v[56:57], v[124:125]
	v_pk_fma_f32 v[50:51], v[50:51], v[58:59], v[126:127]
	v_cvt_pk_bf16_f32 v48, v48, v49
	v_mov_b32_e32 v56, v36
	v_cvt_pk_bf16_f32 v49, v50, v51
	global_store_dwordx2 v[86:87], v[48:49], off offset:1536
	v_mov_b64_e32 v[86:87], v[78:79]
	v_mov_b32_e32 v57, v37
	v_mov_b32_e32 v58, v38
	v_mov_b32_e32 v59, v39
	v_mov_b32_e32 v52, v40
	v_mov_b32_e32 v53, v41
	v_mov_b32_e32 v54, v42
	v_mov_b32_e32 v55, v43
	v_mov_b32_e32 v48, v44
	v_mov_b32_e32 v49, v45
	v_mov_b32_e32 v50, v46
	v_mov_b32_e32 v51, v47
	s_cbranch_vccnz .LBB0_308

; __device__ __forceinline__ unsigned cvt_pk_bf16(float lo, float hi) { unsigned r; asm volatile("s_nop 0\n\tv_cvt_pk_bf16_f32 %0, %1, %2\n\ts_nop 1" : "=v"(r) : "v"(lo), "v"(hi)); return r; }
; __device__ __forceinline__ void phase_ln0(const Params& p, int g, int gw, int NGW, int lane) {
;     ...
;     for (int row = gw; row < RG; row += NGW) {
;         const int mrow = (row < CGR) ? 32 : g * BG + (row - CGR) / SEQ;
;         const float* sh = mod + (size_t)mrow * MODW; const float* sc = sh + DM;
;         f32x4 v[4]; float s = 0.f;
; #pragma unroll
;         for (int j = 0; j < 4; ++j) { v[j] = nx[j]; s += (v[j].x + v[j].y) + (v[j].z + v[j].w); }
;         if (row + NGW < RG) { const float* src = ln0_src(p, g, row + NGW);
; #pragma unroll
;             for (int j = 0; j < 4; ++j) nx[j] = *(const f32x4*)(src + 4 * lane + 256 * j); }
;         const float mean = wave_sum(s, lane) * (1.f / DM); float s2 = 0.f;
; #pragma unroll
;         for (int j = 0; j < 4; ++j) { v[j] = v[j] - mean; s2 += (v[j].x * v[j].x + v[j].y * v[j].y) + (v[j].z * v[j].z + v[j].w * v[j].w); }
;         const float rstd = __builtin_amdgcn_rsqf(wave_sum(s2, lane) * (1.f / DM) + 1e-6f);
; #pragma unroll
;         for (int j = 0; j < 4; ++j) { const int col = 4 * lane + 256 * j; const f32x4 a = *(const f32x4*)(sc + col), b = *(const f32x4*)(sh + col);
;             const f32x4 o = v[j] * rstd * (a + 1.f) + b; u32x2 w; w.x = cvt_pk_bf16(o.x, o.y); w.y = cvt_pk_bf16(o.z, o.w);
;             *(u32x2*)(h0 + (size_t)row * DM + col) = w; }
.LBB0_679:
	v_add_f32_e32 v44, v12, v13
	v_add_f32_e32 v45, v14, v15
	v_add_f32_e32 v44, v44, v45
	v_add_f32_e32 v45, v8, v9
	v_add_f32_e32 v46, v10, v11
	v_add_f32_e32 v44, 0, v44
	v_add_f32_e32 v45, v45, v46
	v_add_f32_e32 v44, v45, v44
	v_add_f32_e32 v45, v4, v5
	v_add_f32_e32 v46, v6, v7
	v_add_f32_e32 v45, v45, v46
	v_add_f32_e32 v44, v45, v44
	v_add_f32_e32 v45, v0, v1
	v_add_f32_e32 v46, v2, v3
	v_add_f32_e32 v45, v45, v46
	v_add_f32_e32 v44, v45, v44
	s_lshl_b64 s[2:3], s[2:3], 2
	s_add_u32 s2, s94, s2
	s_addc_u32 s3, s95, s3
	s_add_u32 s4, s2, 0x1000
	s_nop 1
	v_add_f32_dpp v44, v44, v44 quad_perm:[1,0,3,2] row_mask:0xf bank_mask:0xf
	s_addc_u32 s5, s3, 0
	s_and_b64 vcc, exec, s[0:1]
	v_readlane_b32 s0, v255, 2
	v_readlane_b32 s1, v255, 3
	s_nop 1
	v_add_f32_dpp v44, v44, v44 quad_perm:[2,3,0,1] row_mask:0xf bank_mask:0xf
	s_nop 1
	v_add_f32_dpp v44, v44, v44 row_half_mirror row_mask:0xf bank_mask:0xf
	s_nop 1
	v_add_f32_dpp v44, v44, v44 row_mirror row_mask:0xf bank_mask:0xf
	v_mov_b32_e32 v45, v44
	s_nop 1
	v_permlane16_swap_b32_e32 v44, v45
	v_add_f32_e32 v52, v44, v45
	global_load_dwordx4 v[44:47], v40, s[4:5]
	global_load_dwordx4 v[48:51], v40, s[2:3]
	global_load_dwordx4 v[100:103], v41, s[4:5]
	global_load_dwordx4 v[104:107], v40, s[2:3] offset:1024
	global_load_dwordx4 v[108:111], v42, s[4:5]
	global_load_dwordx4 v[112:115], v40, s[2:3] offset:2048
	global_load_dwordx4 v[116:119], v43, s[4:5]
	global_load_dwordx4 v[120:123], v40, s[2:3] offset:3072
	v_mov_b32_e32 v53, v52
	s_nop 1
	v_permlane32_swap_b32_e32 v52, v53
	v_add_f32_e32 v60, v52, v53
	v_fmac_f32_e32 v13, 0xba800000, v60
	v_fmac_f32_e32 v12, 0xba800000, v60
	v_fmac_f32_e32 v15, 0xba800000, v60
	v_fmac_f32_e32 v14, 0xba800000, v60
	v_pk_mul_f32 v[52:53], v[14:15], v[14:15]
	v_pk_mul_f32 v[54:55], v[12:13], v[12:13]
	v_fmac_f32_e32 v9, 0xba800000, v60
	v_pk_mov_b32 v[56:57], v[54:55], v[52:53] op_sel:[1,0]
	v_mov_b32_e32 v55, v53
	v_fmac_f32_e32 v8, 0xba800000, v60
	v_pk_add_f32 v[52:53], v[56:57], v[54:55]
	v_fmac_f32_e32 v11, 0xba800000, v60
	v_fmac_f32_e32 v10, 0xba800000, v60
	v_pk_add_f32 v[52:53], v[52:53], v[52:53] op_sel_hi:[0,1]
	v_pk_mul_f32 v[54:55], v[10:11], v[10:11]
	v_pk_mul_f32 v[56:57], v[8:9], v[8:9]
	v_fmac_f32_e32 v4, 0xba800000, v60
	v_pk_mov_b32 v[58:59], v[56:57], v[54:55] op_sel:[1,0]
	v_mov_b32_e32 v57, v55
	v_fmac_f32_e32 v5, 0xba800000, v60
	v_fmac_f32_e32 v6, 0xba800000, v60
	v_mul_f32_e32 v52, v4, v4
	v_pk_add_f32 v[54:55], v[58:59], v[56:57]
	v_fmac_f32_e32 v7, 0xba800000, v60
	v_pk_fma_f32 v[56:57], v[4:5], v[4:5], v[52:53] op_sel_hi:[1,1,0]
	v_mul_f32_e32 v52, v6, v6
	v_pk_add_f32 v[54:55], v[54:55], v[54:55] op_sel_hi:[0,1]
	v_pk_fma_f32 v[58:59], v[6:7], v[6:7], v[52:53] op_sel_hi:[1,1,0]
	v_fmac_f32_e32 v3, 0xba800000, v60
	v_fmac_f32_e32 v2, 0xba800000, v60
	v_fmac_f32_e32 v1, 0xba800000, v60
	v_fmac_f32_e32 v0, 0xba800000, v60
	v_mul_f32_e32 v56, v0, v0
	v_mul_f32_e32 v58, v1, v1
	v_mul_f32_e32 v52, v2, v2
	v_mul_f32_e32 v54, v3, v3
	v_pk_add_f32 v[56:57], v[56:57], v[58:59]
	v_pk_add_f32 v[52:53], v[52:53], v[54:55]
	s_waitcnt vmcnt(0)
	v_pk_add_f32 v[44:45], v[44:45], 1.0 op_sel_hi:[1,0]
	v_pk_add_f32 v[52:53], v[56:57], v[52:53]
	v_pk_add_f32 v[46:47], v[46:47], 1.0 op_sel_hi:[1,0]
	v_add_f32_e32 v52, v52, v53
	s_nop 1
	v_add_f32_dpp v52, v52, v52 quad_perm:[1,0,3,2] row_mask:0xf bank_mask:0xf
	s_nop 1
	v_add_f32_dpp v52, v52, v52 quad_perm:[2,3,0,1] row_mask:0xf bank_mask:0xf
	s_nop 1
	v_add_f32_dpp v52, v52, v52 row_half_mirror row_mask:0xf bank_mask:0xf
	s_nop 1
	v_add_f32_dpp v52, v52, v52 row_mirror row_mask:0xf bank_mask:0xf
	v_mov_b32_e32 v53, v52
	s_nop 1
	v_permlane16_swap_b32_e32 v52, v53
	v_add_f32_e32 v52, v52, v53
	v_mov_b32_e32 v53, v52
	s_nop 1
	v_permlane32_swap_b32_e32 v52, v53
	v_add_f32_e32 v52, v52, v53
	v_fmamk_f32 v52, v52, 0x3a800000, v238
	v_rsq_f32_e32 v52, v52
	s_nop 0
	v_pk_mul_f32 v[12:13], v[12:13], v[52:53] op_sel_hi:[1,0]
	v_pk_mul_f32 v[14:15], v[14:15], v[52:53] op_sel_hi:[1,0]
	v_pk_fma_f32 v[12:13], v[44:45], v[12:13], v[48:49]
	v_pk_fma_f32 v[14:15], v[46:47], v[14:15], v[50:51]
	v_cvt_pk_bf16_f32 v12, v12, v13
	v_pk_mul_f32 v[8:9], v[8:9], v[52:53] op_sel_hi:[1,0]
	v_cvt_pk_bf16_f32 v13, v14, v15
	global_store_dwordx2 v[32:33], v[12:13], off
	s_nop 0
	v_pk_mul_f32 v[10:11], v[10:11], v[52:53] op_sel_hi:[1,0]
	v_pk_mul_f32 v[4:5], v[4:5], v[52:53] op_sel_hi:[1,0]
	v_pk_mul_f32 v[6:7], v[6:7], v[52:53] op_sel_hi:[1,0]
	v_pk_mul_f32 v[54:55], v[0:1], v[52:53] op_sel_hi:[1,0]
	v_pk_mul_f32 v[52:53], v[2:3], v[52:53] op_sel_hi:[1,0]
	v_mov_b32_e32 v0, v28
	v_mov_b32_e32 v1, v29
	v_mov_b32_e32 v2, v30
	v_mov_b32_e32 v3, v31
	v_pk_add_f32 v[12:13], v[100:101], 1.0 op_sel_hi:[1,0]
	v_pk_add_f32 v[14:15], v[102:103], 1.0 op_sel_hi:[1,0]
	v_pk_fma_f32 v[8:9], v[12:13], v[8:9], v[104:105]
	v_pk_fma_f32 v[10:11], v[14:15], v[10:11], v[106:107]
	v_cvt_pk_bf16_f32 v8, v8, v9
	s_nop 0
	v_cvt_pk_bf16_f32 v9, v10, v11
	global_store_dwordx2 v[32:33], v[8:9], off offset:512
	s_nop 0
	v_pk_add_f32 v[8:9], v[108:109], 1.0 op_sel_hi:[1,0]
	v_pk_add_f32 v[10:11], v[110:111], 1.0 op_sel_hi:[1,0]
	v_pk_fma_f32 v[4:5], v[8:9], v[4:5], v[112:113]
	v_pk_fma_f32 v[6:7], v[10:11], v[6:7], v[114:115]
	v_cvt_pk_bf16_f32 v4, v4, v5
	v_mov_b32_e32 v14, v18
	v_cvt_pk_bf16_f32 v5, v6, v7
	global_store_dwordx2 v[32:33], v[4:5], off offset:1024
	v_mov_b32_e32 v15, v19
	v_mov_b32_e32 v12, v16
	v_mov_b32_e32 v13, v17
	v_mov_b32_e32 v8, v20
	v_mov_b32_e32 v9, v21
	v_mov_b32_e32 v10, v22
	v_mov_b32_e32 v11, v23
	v_mov_b32_e32 v4, v24
	v_mov_b32_e32 v5, v25
	v_mov_b32_e32 v6, v26
	v_mov_b32_e32 v7, v27
	v_pk_add_f32 v[18:19], v[116:117], 1.0 op_sel_hi:[1,0]
	v_pk_add_f32 v[16:17], v[118:119], 1.0 op_sel_hi:[1,0]
	v_pk_fma_f32 v[18:19], v[18:19], v[54:55], v[120:121]
	v_pk_fma_f32 v[16:17], v[16:17], v[52:53], v[122:123]
	v_cvt_pk_bf16_f32 v18, v18, v19
	s_nop 0
	v_cvt_pk_bf16_f32 v19, v16, v17
	global_store_dwordx2 v[32:33], v[18:19], off offset:1536
	v_lshl_add_u64 v[32:33], v[32:33], 0, s[0:1]
	s_cbranch_vccnz .LBB0_684
